# v30: attention tile-loop latch bookkeeping moved in front of the end-of-step barrier, on top of v27
# baseline (speedup 1.0000x reference)
;     ...
;     for (int i = 0; i < ntiles; ++i) {
.Latt_latch_post:
	s_cbranch_scc0 .LBB0_359

; #define ATT_WAITBAR(n) do { asm volatile("s_waitcnt vmcnt(" #n ") lgkmcnt(0)" ::: "memory"); __builtin_amdgcn_s_barrier(); asm volatile("" ::: "memory"); } while (0)
;     ...
;         if (i + 2 < ntiles) ATT_WAITBAR(4); else ATT_WAITBAR(0);
;         b = (b == 2) ? 0 : b + 1;
.LBB0_418:
	s_add_i32 s2, s75, 1
	s_cmp_lg_u32 s75, 2
	s_cselect_b32 s75, s2, 0
	s_add_i32 s77, s77, 1
	s_add_i32 s74, s74, 64
	s_add_i32 s2, s76, s77
	v_lshl_add_u64 v[150:151], v[150:151], 0, s[54:55]
	v_lshl_add_u64 v[152:153], v[152:153], 0, s[54:55]
	v_lshl_add_u64 v[156:157], v[156:157], 0, s[62:63]
	s_cmp_lg_u32 s2, 4
	v_lshl_add_u64 v[158:159], v[158:159], 0, s[62:63]
	s_waitcnt vmcnt(0) lgkmcnt(0)
	s_barrier
	s_cbranch_execnz .Latt_latch_post
.LBB0_419:
	s_add_i32 s2, s75, 1
	s_cmp_lg_u32 s75, 2
	s_cselect_b32 s75, s2, 0
	s_add_i32 s77, s77, 1
	s_add_i32 s74, s74, 64
	s_add_i32 s2, s76, s77
	v_lshl_add_u64 v[150:151], v[150:151], 0, s[54:55]
	v_lshl_add_u64 v[152:153], v[152:153], 0, s[54:55]
	v_lshl_add_u64 v[156:157], v[156:157], 0, s[62:63]
	s_cmp_lg_u32 s2, 4
	v_lshl_add_u64 v[158:159], v[158:159], 0, s[62:63]
	s_waitcnt vmcnt(4) lgkmcnt(0)
	s_barrier
	s_branch .Latt_latch_post
